# v072 + ssm chunk recurrence (wave 0, 256 dependent steps): z reads software-pipelined one 8-chunk block ahead in dead registers, no LDS wait on the dependent chain
# baseline (speedup 1.0000x reference)
; __device__ __forceinline__ void ssm_v2(const KA& A, const Ctx& F, int l, int b, int g) {
;     ...
;     if (w == 0 && (sp_ & 2)) { const float lr = lam[lane], li = lam[64 + lane]; float xr = 0.f, xi = 0.f;
; #pragma unroll 8
;         for (int j = 0; j < 256; ++j) { const float zr = ZF[j * ZS + lane], zi = ZF[j * ZS + 64 + lane];
;             ZF[j * ZS + lane] = xr; ZF[j * ZS + 64 + lane] = xi;
;             const float nr = lr * xr - li * xi + zr, ni = lr * xi + li * xr + zi; xr = nr; xi = ni; } }
.LBB0_177:
	s_andn2_b64 vcc, exec, s[0:1]
	s_cbranch_vccnz .LBB0_180
	v_lshlrev_b32_e32 v6, 2, v114
	v_mov_b32_e32 v7, v81
	v_lshl_add_u64 v[0:1], s[4:5], 0, v[6:7]
	s_mov_b64 s[0:1], 0x40000
	v_lshl_add_u64 v[2:3], v[0:1], 0, s[0:1]
	v_add_co_u32_e32 v0, vcc, 0x40000, v0
	v_mov_b32_e32 v4, 0
	s_nop 0
	v_addc_co_u32_e32 v1, vcc, 0, v1, vcc
	global_load_dword v0, v[0:1], off
	s_nop 0
	global_load_dword v2, v[2:3], off offset:256
	v_mov_b32_e32 v115, v81
	s_mov_b32 s0, 0
	v_add_u32_e32 v6, 0, v6
	v_mov_b32_e32 v5, v4
	s_waitcnt vmcnt(1)
	v_mov_b32_e32 v1, v0
	s_waitcnt vmcnt(0)
	v_mov_b32_e32 v3, v2
	v_add_u32_e32 v7, s0, v6
	ds_read2st64_b32 v[132:133], v7 offset1:1
	ds_read2_b32 v[134:135], v7 offset0:132 offset1:196
	v_add_u32_e32 v166, 0x20, v7
	ds_read2st64_b32 v[136:137], v166 offset0:4 offset1:5
	v_add_u32_e32 v166, 0x30, v7
	ds_read2st64_b32 v[138:139], v166 offset0:6 offset1:7
	v_add_u32_e32 v166, 0x40, v7
	ds_read2st64_b32 v[140:141], v166 offset0:8 offset1:9
	v_add_u32_e32 v166, 0x50, v7
	ds_read2st64_b32 v[142:143], v166 offset0:10 offset1:11
	v_add_u32_e32 v166, 0x60, v7
	ds_read2st64_b32 v[144:145], v166 offset0:12 offset1:13
	v_add_u32_e32 v166, 0x70, v7
	ds_read2st64_b32 v[146:147], v166 offset0:14 offset1:15
.Lssm_rec:
	v_add_u32_e32 v164, 0x1080, v7
	ds_read2st64_b32 v[148:149], v164 offset1:1
	ds_read2_b32 v[150:151], v164 offset0:132 offset1:196
	v_add_u32_e32 v166, 0x20, v164
	ds_read2st64_b32 v[152:153], v166 offset0:4 offset1:5
	v_add_u32_e32 v166, 0x30, v164
	ds_read2st64_b32 v[154:155], v166 offset0:6 offset1:7
	v_add_u32_e32 v166, 0x40, v164
	ds_read2st64_b32 v[156:157], v166 offset0:8 offset1:9
	v_add_u32_e32 v166, 0x50, v164
	ds_read2st64_b32 v[158:159], v166 offset0:10 offset1:11
	v_add_u32_e32 v166, 0x60, v164
	ds_read2st64_b32 v[160:161], v166 offset0:12 offset1:13
	v_add_u32_e32 v166, 0x70, v164
	ds_read2st64_b32 v[162:163], v166 offset0:14 offset1:15
	s_waitcnt lgkmcnt(8)
	v_pk_mul_f32 v[10:11], v[2:3], v[4:5] op_sel:[0,1] op_sel_hi:[1,0]
	ds_write2st64_b32 v7, v4, v5 offset1:1
	v_pk_fma_f32 v[12:13], v[0:1], v[4:5], v[10:11] neg_lo:[0,0,1] neg_hi:[0,0,1]
	v_pk_fma_f32 v[4:5], v[0:1], v[4:5], v[10:11]
	s_nop 0
	v_mov_b32_e32 v13, v5
	s_nop 0
	v_pk_add_f32 v[4:5], v[12:13], v[132:133]
	s_nop 0
	v_pk_mul_f32 v[10:11], v[2:3], v[4:5] op_sel:[0,1] op_sel_hi:[1,0]
	ds_write2_b32 v7, v4, v5 offset0:132 offset1:196
	v_pk_fma_f32 v[12:13], v[0:1], v[4:5], v[10:11] neg_lo:[0,0,1] neg_hi:[0,0,1]
	v_pk_fma_f32 v[4:5], v[0:1], v[4:5], v[10:11]
	v_add_u32_e32 v165, 0x20, v7
	v_mov_b32_e32 v13, v5
	s_nop 0
	v_pk_add_f32 v[4:5], v[12:13], v[134:135]
	s_nop 0
	v_pk_mul_f32 v[10:11], v[2:3], v[4:5] op_sel:[0,1] op_sel_hi:[1,0]
	ds_write2st64_b32 v165, v4, v5 offset0:4 offset1:5
	v_pk_fma_f32 v[12:13], v[0:1], v[4:5], v[10:11] neg_lo:[0,0,1] neg_hi:[0,0,1]
	v_pk_fma_f32 v[4:5], v[0:1], v[4:5], v[10:11]
	v_add_u32_e32 v165, 0x30, v7
	v_mov_b32_e32 v13, v5
	s_nop 0
	v_pk_add_f32 v[4:5], v[12:13], v[136:137]
	s_nop 0
	v_pk_mul_f32 v[10:11], v[2:3], v[4:5] op_sel:[0,1] op_sel_hi:[1,0]
	ds_write2st64_b32 v165, v4, v5 offset0:6 offset1:7
	v_pk_fma_f32 v[12:13], v[0:1], v[4:5], v[10:11] neg_lo:[0,0,1] neg_hi:[0,0,1]
	v_pk_fma_f32 v[4:5], v[0:1], v[4:5], v[10:11]
	v_add_u32_e32 v165, 0x40, v7
	v_mov_b32_e32 v13, v5
	s_nop 0
	v_pk_add_f32 v[4:5], v[12:13], v[138:139]
	s_nop 0
	v_pk_mul_f32 v[10:11], v[2:3], v[4:5] op_sel:[0,1] op_sel_hi:[1,0]
	ds_write2st64_b32 v165, v4, v5 offset0:8 offset1:9
	v_pk_fma_f32 v[12:13], v[0:1], v[4:5], v[10:11] neg_lo:[0,0,1] neg_hi:[0,0,1]
	v_pk_fma_f32 v[4:5], v[0:1], v[4:5], v[10:11]
	v_add_u32_e32 v165, 0x50, v7
	v_mov_b32_e32 v13, v5
	s_nop 0
	v_pk_add_f32 v[4:5], v[12:13], v[140:141]
	s_nop 0
	v_pk_mul_f32 v[10:11], v[2:3], v[4:5] op_sel:[0,1] op_sel_hi:[1,0]
	ds_write2st64_b32 v165, v4, v5 offset0:10 offset1:11
	v_pk_fma_f32 v[12:13], v[0:1], v[4:5], v[10:11] neg_lo:[0,0,1] neg_hi:[0,0,1]
	v_pk_fma_f32 v[4:5], v[0:1], v[4:5], v[10:11]
	v_add_u32_e32 v165, 0x60, v7
	v_mov_b32_e32 v13, v5
	s_nop 0
	v_pk_add_f32 v[4:5], v[12:13], v[142:143]
	s_nop 0
	v_pk_mul_f32 v[10:11], v[2:3], v[4:5] op_sel:[0,1] op_sel_hi:[1,0]
	ds_write2st64_b32 v165, v4, v5 offset0:12 offset1:13
	v_pk_fma_f32 v[12:13], v[0:1], v[4:5], v[10:11] neg_lo:[0,0,1] neg_hi:[0,0,1]
	v_pk_fma_f32 v[4:5], v[0:1], v[4:5], v[10:11]
	v_add_u32_e32 v165, 0x70, v7
	v_mov_b32_e32 v13, v5
	s_nop 0
	v_pk_add_f32 v[4:5], v[12:13], v[144:145]
	s_nop 0
	v_pk_mul_f32 v[10:11], v[2:3], v[4:5] op_sel:[0,1] op_sel_hi:[1,0]
	ds_write2st64_b32 v165, v4, v5 offset0:14 offset1:15
	v_pk_fma_f32 v[12:13], v[0:1], v[4:5], v[10:11] neg_lo:[0,0,1] neg_hi:[0,0,1]
	v_pk_fma_f32 v[4:5], v[0:1], v[4:5], v[10:11]
	s_nop 0
	v_mov_b32_e32 v13, v5
	s_nop 0
	v_pk_add_f32 v[4:5], v[12:13], v[146:147]
	s_nop 0
	v_add_u32_e32 v7, 0x1080, v164
	ds_read2st64_b32 v[132:133], v7 offset1:1
	ds_read2_b32 v[134:135], v7 offset0:132 offset1:196
	v_add_u32_e32 v166, 0x20, v7
	ds_read2st64_b32 v[136:137], v166 offset0:4 offset1:5
	v_add_u32_e32 v166, 0x30, v7
	ds_read2st64_b32 v[138:139], v166 offset0:6 offset1:7
	v_add_u32_e32 v166, 0x40, v7
	ds_read2st64_b32 v[140:141], v166 offset0:8 offset1:9
	v_add_u32_e32 v166, 0x50, v7
	ds_read2st64_b32 v[142:143], v166 offset0:10 offset1:11
	v_add_u32_e32 v166, 0x60, v7
	ds_read2st64_b32 v[144:145], v166 offset0:12 offset1:13
	v_add_u32_e32 v166, 0x70, v7
	ds_read2st64_b32 v[146:147], v166 offset0:14 offset1:15
	s_waitcnt lgkmcnt(8)
; __device__ __forceinline__ void ssm_v2(const KA& A, const Ctx& F, int l, int b, int g) {
;     ...
;     if (w == 0 && (sp_ & 2)) { const float lr = lam[lane], li = lam[64 + lane]; float xr = 0.f, xi = 0.f;
; #pragma unroll 8
;         for (int j = 0; j < 256; ++j) { const float zr = ZF[j * ZS + lane], zi = ZF[j * ZS + 64 + lane];
;             ZF[j * ZS + lane] = xr; ZF[j * ZS + 64 + lane] = xi;
;             const float nr = lr * xr - li * xi + zr, ni = lr * xi + li * xr + zi; xr = nr; xi = ni; } }
	v_pk_mul_f32 v[10:11], v[2:3], v[4:5] op_sel:[0,1] op_sel_hi:[1,0]
	ds_write2st64_b32 v164, v4, v5 offset1:1
	v_pk_fma_f32 v[12:13], v[0:1], v[4:5], v[10:11] neg_lo:[0,0,1] neg_hi:[0,0,1]
	v_pk_fma_f32 v[4:5], v[0:1], v[4:5], v[10:11]
	s_nop 0
	v_mov_b32_e32 v13, v5
	s_nop 0
	v_pk_add_f32 v[4:5], v[12:13], v[148:149]
	s_nop 0
	v_pk_mul_f32 v[10:11], v[2:3], v[4:5] op_sel:[0,1] op_sel_hi:[1,0]
	ds_write2_b32 v164, v4, v5 offset0:132 offset1:196
	v_pk_fma_f32 v[12:13], v[0:1], v[4:5], v[10:11] neg_lo:[0,0,1] neg_hi:[0,0,1]
	v_pk_fma_f32 v[4:5], v[0:1], v[4:5], v[10:11]
	v_add_u32_e32 v165, 0x20, v164
	v_mov_b32_e32 v13, v5
	s_nop 0
	v_pk_add_f32 v[4:5], v[12:13], v[150:151]
	s_nop 0
	v_pk_mul_f32 v[10:11], v[2:3], v[4:5] op_sel:[0,1] op_sel_hi:[1,0]
	ds_write2st64_b32 v165, v4, v5 offset0:4 offset1:5
	v_pk_fma_f32 v[12:13], v[0:1], v[4:5], v[10:11] neg_lo:[0,0,1] neg_hi:[0,0,1]
	v_pk_fma_f32 v[4:5], v[0:1], v[4:5], v[10:11]
	v_add_u32_e32 v165, 0x30, v164
	v_mov_b32_e32 v13, v5
	s_nop 0
	v_pk_add_f32 v[4:5], v[12:13], v[152:153]
	s_nop 0
	v_pk_mul_f32 v[10:11], v[2:3], v[4:5] op_sel:[0,1] op_sel_hi:[1,0]
	ds_write2st64_b32 v165, v4, v5 offset0:6 offset1:7
	v_pk_fma_f32 v[12:13], v[0:1], v[4:5], v[10:11] neg_lo:[0,0,1] neg_hi:[0,0,1]
	v_pk_fma_f32 v[4:5], v[0:1], v[4:5], v[10:11]
	v_add_u32_e32 v165, 0x40, v164
	v_mov_b32_e32 v13, v5
	s_nop 0
	v_pk_add_f32 v[4:5], v[12:13], v[154:155]
	s_nop 0
	v_pk_mul_f32 v[10:11], v[2:3], v[4:5] op_sel:[0,1] op_sel_hi:[1,0]
	ds_write2st64_b32 v165, v4, v5 offset0:8 offset1:9
	v_pk_fma_f32 v[12:13], v[0:1], v[4:5], v[10:11] neg_lo:[0,0,1] neg_hi:[0,0,1]
	v_pk_fma_f32 v[4:5], v[0:1], v[4:5], v[10:11]
	v_add_u32_e32 v165, 0x50, v164
	v_mov_b32_e32 v13, v5
	s_nop 0
	v_pk_add_f32 v[4:5], v[12:13], v[156:157]
	s_nop 0
	v_pk_mul_f32 v[10:11], v[2:3], v[4:5] op_sel:[0,1] op_sel_hi:[1,0]
	ds_write2st64_b32 v165, v4, v5 offset0:10 offset1:11
	v_pk_fma_f32 v[12:13], v[0:1], v[4:5], v[10:11] neg_lo:[0,0,1] neg_hi:[0,0,1]
	v_pk_fma_f32 v[4:5], v[0:1], v[4:5], v[10:11]
	v_add_u32_e32 v165, 0x60, v164
	v_mov_b32_e32 v13, v5
	s_nop 0
	v_pk_add_f32 v[4:5], v[12:13], v[158:159]
	s_nop 0
	v_pk_mul_f32 v[10:11], v[2:3], v[4:5] op_sel:[0,1] op_sel_hi:[1,0]
	ds_write2st64_b32 v165, v4, v5 offset0:12 offset1:13
	v_pk_fma_f32 v[12:13], v[0:1], v[4:5], v[10:11] neg_lo:[0,0,1] neg_hi:[0,0,1]
	v_pk_fma_f32 v[4:5], v[0:1], v[4:5], v[10:11]
	v_add_u32_e32 v165, 0x70, v164
	v_mov_b32_e32 v13, v5
	s_nop 0
	v_pk_add_f32 v[4:5], v[12:13], v[160:161]
	s_nop 0
	v_pk_mul_f32 v[10:11], v[2:3], v[4:5] op_sel:[0,1] op_sel_hi:[1,0]
	ds_write2st64_b32 v165, v4, v5 offset0:14 offset1:15
	v_pk_fma_f32 v[12:13], v[0:1], v[4:5], v[10:11] neg_lo:[0,0,1] neg_hi:[0,0,1]
	v_pk_fma_f32 v[4:5], v[0:1], v[4:5], v[10:11]
	s_nop 0
	v_mov_b32_e32 v13, v5
	s_nop 0
	v_pk_add_f32 v[4:5], v[12:13], v[162:163]
	s_nop 0
	s_addk_i32 s0, 0x2100
	s_cmp_lg_u32 s0, 0x21000
	s_cbranch_scc1 .Lssm_rec
